# hottest loop heads (FFN gate/up and down K-loops, attention interior loop) aligned to 64 bytes with s_nop padding
# baseline (speedup 1.0000x reference)
.LBB0_104:
	s_mov_b32 s43, s13
	s_mul_i32 s52, s43, 0x3000
	s_add_i32 s52, s52, 16
	v_add_u32_e32 v174, s52, v149
	ds_read_b128 v[204:207], v174
	ds_read_b128 v[208:211], v174 offset:32
	ds_read_b128 v[212:215], v174 offset:6144
	ds_read_b128 v[216:219], v174 offset:6176
	ds_read_b128 v[220:223], v174 offset:64
	ds_read_b128 v[224:227], v174 offset:96
	ds_read_b128 v[228:231], v174 offset:6208
	ds_read_b128 v[232:235], v174 offset:6240
	v_add_u32_e32 v175, s52, v150
	ds_read_b128 v[176:179], v175
	ds_read_b128 v[180:183], v175 offset:6144
	v_add_u32_e32 v174, s52, v151
	ds_read_b128 v[184:187], v174
	ds_read_b128 v[188:191], v174 offset:6144
	.p2align	6

.LBB0_192:
	s_add_u32 s74, s54, 0x100
	s_addc_u32 s75, s55, 0
	s_mov_b32 s78, -2
	s_waitcnt lgkmcnt(0)
	s_add_u32 s44, s40, 0x100
	s_addc_u32 s45, s41, 0
	s_add_i32 s76, 16, 0x10000
	s_cmp_eq_u32 s78, 40
	s_cselect_b32 s61, s11, s45
	s_cselect_b32 s60, s10, s44
	v_add_u32_e32 v80, s76, v144
	s_cselect_b32 s55, s15, s75
	s_cselect_b32 s54, s14, s74
	s_add_i32 s77, 16, 0x14000
	ds_read_b128 v[146:149], v80
	ds_read_b128 v[160:163], v80 offset:1024
	ds_read_b128 v[164:167], v80 offset:2048
	ds_read_b128 v[168:171], v80 offset:3072
	v_add_u32_e32 v80, s77, v144
	ds_read_b128 v[172:175], v80
	ds_read_b128 v[176:179], v80 offset:1024
	ds_read_b128 v[180:183], v80 offset:2048
	ds_read_b128 v[184:187], v80 offset:3072
	v_lshl_add_u64 v[142:143], s[40:41], 0, v[138:139]
	s_add_i32 m0, s13, 0xc000
	ds_read_b128 v[188:191], v145
	ds_read_b128 v[204:207], v145 offset:1024
	ds_read_b128 v[214:217], v145 offset:2048
	ds_read_b128 v[218:221], v145 offset:3072
	ds_read_b128 v[222:225], v145 offset:4096
	ds_read_b128 v[226:229], v145 offset:5120
	ds_read_b128 v[230:233], v145 offset:6144
	ds_read_b128 v[234:237], v145 offset:7168
	global_load_lds_dwordx4 v[142:143], off
	v_lshl_add_u64 v[142:143], s[40:41], 0, v[140:141]
	s_add_i32 m0, s13, 0xe000
	s_nop 0
	global_load_lds_dwordx4 v[142:143], off
	s_waitcnt vmcnt(8)
	s_waitcnt lgkmcnt(0)
	s_barrier
	s_waitcnt lgkmcnt(0)
	v_mfma_f32_16x16x32_bf16 v[126:129], v[146:149], v[188:191], 0
	v_mfma_f32_16x16x32_bf16 v[122:125], v[164:167], v[188:191], 0
	v_mfma_f32_16x16x32_bf16 v[110:113], v[146:149], v[214:217], 0
	v_mfma_f32_16x16x32_bf16 v[106:109], v[164:167], v[214:217], 0
	v_mfma_f32_16x16x32_bf16 v[94:97], v[146:149], v[222:225], 0
	v_mfma_f32_16x16x32_bf16 v[90:93], v[164:167], v[222:225], 0
	v_mfma_f32_16x16x32_bf16 v[76:79], v[146:149], v[230:233], 0
	v_mfma_f32_16x16x32_bf16 v[72:75], v[164:167], v[230:233], 0
	v_mfma_f32_16x16x32_bf16 v[126:129], v[160:163], v[204:207], v[126:129]
	v_mfma_f32_16x16x32_bf16 v[122:125], v[168:171], v[204:207], v[122:125]
	v_mfma_f32_16x16x32_bf16 v[110:113], v[160:163], v[218:221], v[110:113]
	v_mfma_f32_16x16x32_bf16 v[106:109], v[168:171], v[218:221], v[106:109]
	v_mfma_f32_16x16x32_bf16 v[94:97], v[160:163], v[226:229], v[94:97]
	v_mfma_f32_16x16x32_bf16 v[90:93], v[168:171], v[226:229], v[90:93]
	v_mfma_f32_16x16x32_bf16 v[76:79], v[160:163], v[234:237], v[76:79]
	v_mfma_f32_16x16x32_bf16 v[72:75], v[168:171], v[234:237], v[72:75]
	v_mfma_f32_16x16x32_bf16 v[118:121], v[172:175], v[188:191], 0
	v_mfma_f32_16x16x32_bf16 v[114:117], v[180:183], v[188:191], 0
	v_mfma_f32_16x16x32_bf16 v[102:105], v[172:175], v[214:217], 0
	v_mfma_f32_16x16x32_bf16 v[98:101], v[180:183], v[214:217], 0
	v_mfma_f32_16x16x32_bf16 v[86:89], v[172:175], v[222:225], 0
	v_mfma_f32_16x16x32_bf16 v[82:85], v[180:183], v[222:225], 0
	v_mfma_f32_16x16x32_bf16 v[68:71], v[172:175], v[230:233], 0
	v_mfma_f32_16x16x32_bf16 v[64:67], v[180:183], v[230:233], 0
	v_mfma_f32_16x16x32_bf16 v[118:121], v[176:179], v[204:207], v[118:121]
	v_mfma_f32_16x16x32_bf16 v[114:117], v[184:187], v[204:207], v[114:117]
	v_mfma_f32_16x16x32_bf16 v[102:105], v[176:179], v[218:221], v[102:105]
	v_mfma_f32_16x16x32_bf16 v[98:101], v[184:187], v[218:221], v[98:101]
	v_mfma_f32_16x16x32_bf16 v[86:89], v[176:179], v[226:229], v[86:89]
	v_mfma_f32_16x16x32_bf16 v[82:85], v[184:187], v[226:229], v[82:85]
	v_mfma_f32_16x16x32_bf16 v[68:71], v[176:179], v[234:237], v[68:71]
	v_mfma_f32_16x16x32_bf16 v[64:67], v[184:187], v[234:237], v[64:67]
	s_barrier
	s_add_i32 s40, s76, s4
	v_lshl_add_u64 v[142:143], s[54:55], 0, v[134:135]
	s_mov_b32 m0, s40
	ds_read_b128 v[188:191], v145 offset:16384
	ds_read_b128 v[204:207], v145 offset:17408
	ds_read_b128 v[214:217], v145 offset:18432
	ds_read_b128 v[218:221], v145 offset:19456
	ds_read_b128 v[222:225], v145 offset:20480
	ds_read_b128 v[226:229], v145 offset:21504
	ds_read_b128 v[230:233], v145 offset:22528
	ds_read_b128 v[234:237], v145 offset:23552
	global_load_lds_dwordx4 v[142:143], off
	s_add_i32 m0, s40, 0x2000
	s_add_u32 s40, s54, 0xb0000
	v_lshl_add_u64 v[150:151], s[54:55], 0, v[130:131]
	s_addc_u32 s41, s55, 0
	s_add_i32 s76, s77, s4
	global_load_lds_dwordx4 v[150:151], off
	v_lshl_add_u64 v[208:209], s[40:41], 0, v[134:135]
	s_mov_b32 m0, s76
	v_lshl_add_u64 v[238:239], s[60:61], 0, v[132:133]
	global_load_lds_dwordx4 v[208:209], off
	v_lshl_add_u64 v[208:209], s[40:41], 0, v[130:131]
	s_add_i32 m0, s76, 0x2000
	s_nop 0
	global_load_lds_dwordx4 v[208:209], off
	v_lshl_add_u64 v[208:209], s[60:61], 0, v[136:137]
	s_mov_b32 m0, s13
	s_nop 0
	global_load_lds_dwordx4 v[208:209], off
	s_mov_b32 m0, s25
	s_nop 0
	global_load_lds_dwordx4 v[238:239], off
	s_waitcnt vmcnt(8)
	s_waitcnt lgkmcnt(0)
	s_barrier
	s_waitcnt lgkmcnt(0)
	v_mfma_f32_16x16x32_bf16 v[60:63], v[146:149], v[188:191], 0
	v_mfma_f32_16x16x32_bf16 v[56:59], v[164:167], v[188:191], 0
	v_mfma_f32_16x16x32_bf16 v[44:47], v[146:149], v[214:217], 0
	v_mfma_f32_16x16x32_bf16 v[40:43], v[164:167], v[214:217], 0
	v_mfma_f32_16x16x32_bf16 v[28:31], v[146:149], v[222:225], 0
	v_mfma_f32_16x16x32_bf16 v[24:27], v[164:167], v[222:225], 0
	v_mfma_f32_16x16x32_bf16 v[12:15], v[146:149], v[230:233], 0
	v_mfma_f32_16x16x32_bf16 v[8:11], v[164:167], v[230:233], 0
	v_mfma_f32_16x16x32_bf16 v[60:63], v[160:163], v[204:207], v[60:63]
	v_mfma_f32_16x16x32_bf16 v[56:59], v[168:171], v[204:207], v[56:59]
	v_mfma_f32_16x16x32_bf16 v[44:47], v[160:163], v[218:221], v[44:47]
	v_mfma_f32_16x16x32_bf16 v[40:43], v[168:171], v[218:221], v[40:43]
	v_mfma_f32_16x16x32_bf16 v[28:31], v[160:163], v[226:229], v[28:31]
	v_mfma_f32_16x16x32_bf16 v[24:27], v[168:171], v[226:229], v[24:27]
	v_mfma_f32_16x16x32_bf16 v[12:15], v[160:163], v[234:237], v[12:15]
	v_mfma_f32_16x16x32_bf16 v[8:11], v[168:171], v[234:237], v[8:11]
	v_mfma_f32_16x16x32_bf16 v[52:55], v[172:175], v[188:191], 0
	v_mfma_f32_16x16x32_bf16 v[48:51], v[180:183], v[188:191], 0
	v_mfma_f32_16x16x32_bf16 v[36:39], v[172:175], v[214:217], 0
	v_mfma_f32_16x16x32_bf16 v[32:35], v[180:183], v[214:217], 0
	v_mfma_f32_16x16x32_bf16 v[20:23], v[172:175], v[222:225], 0
	v_mfma_f32_16x16x32_bf16 v[16:19], v[180:183], v[222:225], 0
	v_mfma_f32_16x16x32_bf16 v[4:7], v[172:175], v[230:233], 0
	v_mfma_f32_16x16x32_bf16 v[0:3], v[180:183], v[230:233], 0
	v_mfma_f32_16x16x32_bf16 v[52:55], v[176:179], v[204:207], v[52:55]
	v_mfma_f32_16x16x32_bf16 v[48:51], v[184:187], v[204:207], v[48:51]
	v_mfma_f32_16x16x32_bf16 v[36:39], v[176:179], v[218:221], v[36:39]
	v_mfma_f32_16x16x32_bf16 v[32:35], v[184:187], v[218:221], v[32:35]
	v_mfma_f32_16x16x32_bf16 v[20:23], v[176:179], v[226:229], v[20:23]
	v_mfma_f32_16x16x32_bf16 v[16:19], v[184:187], v[226:229], v[16:19]
	v_mfma_f32_16x16x32_bf16 v[4:7], v[176:179], v[234:237], v[4:7]
	v_mfma_f32_16x16x32_bf16 v[0:3], v[184:187], v[234:237], v[0:3]
	s_barrier
	s_add_i32 s76, 16, 0x18000
	v_add_u32_e32 v80, s76, v144
	s_add_i32 s77, 16, 0x1c000
	ds_read_b128 v[146:149], v80
	ds_read_b128 v[160:163], v80 offset:1024
	ds_read_b128 v[164:167], v80 offset:2048
	ds_read_b128 v[168:171], v80 offset:3072
	v_add_u32_e32 v80, s77, v144
	ds_read_b128 v[172:175], v80
	ds_read_b128 v[176:179], v80 offset:1024
	ds_read_b128 v[180:183], v80 offset:2048
	ds_read_b128 v[184:187], v80 offset:3072
	s_add_u32 s40, s60, 0xb0000
	s_addc_u32 s41, s61, 0
	s_mov_b32 m0, s30
	v_lshl_add_u64 v[240:241], s[40:41], 0, v[136:137]
	ds_read_b128 v[188:191], v145 offset:32768
	ds_read_b128 v[204:207], v145 offset:33792
	ds_read_b128 v[214:217], v145 offset:34816
	ds_read_b128 v[218:221], v145 offset:35840
	ds_read_b128 v[222:225], v145 offset:36864
	ds_read_b128 v[226:229], v145 offset:37888
	ds_read_b128 v[230:233], v145 offset:38912
	ds_read_b128 v[234:237], v145 offset:39936
	global_load_lds_dwordx4 v[240:241], off
	v_lshl_add_u64 v[240:241], s[40:41], 0, v[132:133]
	s_mov_b32 m0, s33
	s_nop 0
	global_load_lds_dwordx4 v[240:241], off
	s_waitcnt vmcnt(8)
	s_waitcnt lgkmcnt(0)
	s_barrier
	s_waitcnt lgkmcnt(0)
	v_mfma_f32_16x16x32_bf16 v[126:129], v[146:149], v[188:191], v[126:129]
	v_mfma_f32_16x16x32_bf16 v[122:125], v[164:167], v[188:191], v[122:125]
	v_mfma_f32_16x16x32_bf16 v[110:113], v[146:149], v[214:217], v[110:113]
	v_mfma_f32_16x16x32_bf16 v[106:109], v[164:167], v[214:217], v[106:109]
	v_mfma_f32_16x16x32_bf16 v[94:97], v[146:149], v[222:225], v[94:97]
	v_mfma_f32_16x16x32_bf16 v[90:93], v[164:167], v[222:225], v[90:93]
	v_mfma_f32_16x16x32_bf16 v[76:79], v[146:149], v[230:233], v[76:79]
	v_mfma_f32_16x16x32_bf16 v[72:75], v[164:167], v[230:233], v[72:75]
	v_mfma_f32_16x16x32_bf16 v[126:129], v[160:163], v[204:207], v[126:129]
	v_mfma_f32_16x16x32_bf16 v[122:125], v[168:171], v[204:207], v[122:125]
	v_mfma_f32_16x16x32_bf16 v[110:113], v[160:163], v[218:221], v[110:113]
	v_mfma_f32_16x16x32_bf16 v[106:109], v[168:171], v[218:221], v[106:109]
	v_mfma_f32_16x16x32_bf16 v[94:97], v[160:163], v[226:229], v[94:97]
	v_mfma_f32_16x16x32_bf16 v[90:93], v[168:171], v[226:229], v[90:93]
	v_mfma_f32_16x16x32_bf16 v[76:79], v[160:163], v[234:237], v[76:79]
	v_mfma_f32_16x16x32_bf16 v[72:75], v[168:171], v[234:237], v[72:75]
	v_mfma_f32_16x16x32_bf16 v[118:121], v[172:175], v[188:191], v[118:121]
	v_mfma_f32_16x16x32_bf16 v[114:117], v[180:183], v[188:191], v[114:117]
	v_mfma_f32_16x16x32_bf16 v[102:105], v[172:175], v[214:217], v[102:105]
	v_mfma_f32_16x16x32_bf16 v[98:101], v[180:183], v[214:217], v[98:101]
	v_mfma_f32_16x16x32_bf16 v[86:89], v[172:175], v[222:225], v[86:89]
	v_mfma_f32_16x16x32_bf16 v[82:85], v[180:183], v[222:225], v[82:85]
	v_mfma_f32_16x16x32_bf16 v[68:71], v[172:175], v[230:233], v[68:71]
	v_mfma_f32_16x16x32_bf16 v[64:67], v[180:183], v[230:233], v[64:67]
	v_mfma_f32_16x16x32_bf16 v[118:121], v[176:179], v[204:207], v[118:121]
	v_mfma_f32_16x16x32_bf16 v[114:117], v[184:187], v[204:207], v[114:117]
	v_mfma_f32_16x16x32_bf16 v[102:105], v[176:179], v[218:221], v[102:105]
	v_mfma_f32_16x16x32_bf16 v[98:101], v[184:187], v[218:221], v[98:101]
	v_mfma_f32_16x16x32_bf16 v[86:89], v[176:179], v[226:229], v[86:89]
	v_mfma_f32_16x16x32_bf16 v[82:85], v[184:187], v[226:229], v[82:85]
	v_mfma_f32_16x16x32_bf16 v[68:71], v[176:179], v[234:237], v[68:71]
	v_mfma_f32_16x16x32_bf16 v[64:67], v[184:187], v[234:237], v[64:67]
	s_barrier
	s_add_i32 s40, s76, s4
	v_lshl_add_u64 v[142:143], v[142:143], 0, s[20:21]
	s_mov_b32 m0, s40
	ds_read_b128 v[188:191], v145 offset:49152
	ds_read_b128 v[204:207], v145 offset:50176
	ds_read_b128 v[214:217], v145 offset:51200
	ds_read_b128 v[218:221], v145 offset:52224
	ds_read_b128 v[222:225], v145 offset:53248
	ds_read_b128 v[226:229], v145 offset:54272
	ds_read_b128 v[230:233], v145 offset:55296
	ds_read_b128 v[234:237], v145 offset:56320
	global_load_lds_dwordx4 v[142:143], off
	s_add_i32 m0, s40, 0x2000
	s_add_u32 s40, s54, 0xb0080
	v_lshl_add_u64 v[142:143], v[150:151], 0, s[20:21]
	s_addc_u32 s41, s55, 0
	s_add_i32 s54, s77, s4
	global_load_lds_dwordx4 v[142:143], off
	v_lshl_add_u64 v[142:143], s[40:41], 0, v[134:135]
	s_mov_b32 m0, s54
	s_nop 0
	global_load_lds_dwordx4 v[142:143], off
	v_lshl_add_u64 v[142:143], s[40:41], 0, v[130:131]
	s_add_i32 m0, s54, 0x2000
	s_nop 0
	global_load_lds_dwordx4 v[142:143], off
	v_lshl_add_u64 v[142:143], v[208:209], 0, s[20:21]
	s_mov_b32 m0, s34
	s_nop 0
	global_load_lds_dwordx4 v[142:143], off
	v_lshl_add_u64 v[142:143], v[238:239], 0, s[20:21]
	s_mov_b32 m0, s36
	s_nop 0
	global_load_lds_dwordx4 v[142:143], off
	s_waitcnt vmcnt(8)
	s_waitcnt lgkmcnt(0)
	s_barrier
	s_waitcnt lgkmcnt(0)
	v_mfma_f32_16x16x32_bf16 v[60:63], v[146:149], v[188:191], v[60:63]
	v_mfma_f32_16x16x32_bf16 v[56:59], v[164:167], v[188:191], v[56:59]
	v_mfma_f32_16x16x32_bf16 v[44:47], v[146:149], v[214:217], v[44:47]
	v_mfma_f32_16x16x32_bf16 v[40:43], v[164:167], v[214:217], v[40:43]
	v_mfma_f32_16x16x32_bf16 v[28:31], v[146:149], v[222:225], v[28:31]
	v_mfma_f32_16x16x32_bf16 v[24:27], v[164:167], v[222:225], v[24:27]
	v_mfma_f32_16x16x32_bf16 v[12:15], v[146:149], v[230:233], v[12:15]
	v_mfma_f32_16x16x32_bf16 v[8:11], v[164:167], v[230:233], v[8:11]
	v_mfma_f32_16x16x32_bf16 v[60:63], v[160:163], v[204:207], v[60:63]
	v_mfma_f32_16x16x32_bf16 v[56:59], v[168:171], v[204:207], v[56:59]
	v_mfma_f32_16x16x32_bf16 v[44:47], v[160:163], v[218:221], v[44:47]
	v_mfma_f32_16x16x32_bf16 v[40:43], v[168:171], v[218:221], v[40:43]
	v_mfma_f32_16x16x32_bf16 v[28:31], v[160:163], v[226:229], v[28:31]
	v_mfma_f32_16x16x32_bf16 v[24:27], v[168:171], v[226:229], v[24:27]
	v_mfma_f32_16x16x32_bf16 v[12:15], v[160:163], v[234:237], v[12:15]
	v_mfma_f32_16x16x32_bf16 v[8:11], v[168:171], v[234:237], v[8:11]
	v_mfma_f32_16x16x32_bf16 v[52:55], v[172:175], v[188:191], v[52:55]
	v_mfma_f32_16x16x32_bf16 v[48:51], v[180:183], v[188:191], v[48:51]
	v_mfma_f32_16x16x32_bf16 v[36:39], v[172:175], v[214:217], v[36:39]
	v_mfma_f32_16x16x32_bf16 v[32:35], v[180:183], v[214:217], v[32:35]
	v_mfma_f32_16x16x32_bf16 v[20:23], v[172:175], v[222:225], v[20:23]
	v_mfma_f32_16x16x32_bf16 v[16:19], v[180:183], v[222:225], v[16:19]
	v_mfma_f32_16x16x32_bf16 v[4:7], v[172:175], v[230:233], v[4:7]
	v_mfma_f32_16x16x32_bf16 v[0:3], v[180:183], v[230:233], v[0:3]
	v_mfma_f32_16x16x32_bf16 v[52:55], v[176:179], v[204:207], v[52:55]
	v_mfma_f32_16x16x32_bf16 v[48:51], v[184:187], v[204:207], v[48:51]
	v_mfma_f32_16x16x32_bf16 v[36:39], v[176:179], v[218:221], v[36:39]
	v_mfma_f32_16x16x32_bf16 v[32:35], v[184:187], v[218:221], v[32:35]
	v_mfma_f32_16x16x32_bf16 v[20:23], v[176:179], v[226:229], v[20:23]
	v_mfma_f32_16x16x32_bf16 v[16:19], v[184:187], v[226:229], v[16:19]
	v_mfma_f32_16x16x32_bf16 v[4:7], v[176:179], v[234:237], v[4:7]
	v_mfma_f32_16x16x32_bf16 v[0:3], v[184:187], v[234:237], v[0:3]
	s_barrier
	s_add_i32 s78, s78, 2
	s_add_u32 s74, s74, 0x100
	s_addc_u32 s75, s75, 0
	s_cmp_gt_u32 s78, 41
	s_mov_b64 s[40:41], s[44:45]
	.p2align	6

.LBB0_226:
	s_ashr_i32 s15, s14, 31
	s_lshl_b64 s[40:41], s[14:15], 19
	s_add_u32 s40, s38, s40
	s_addc_u32 s41, s39, s41
	s_and_b64 s[42:43], s[44:45], exec
	s_cselect_b32 s15, s41, s47
	s_cselect_b32 s72, s40, s46
	s_ashr_i32 s11, s10, 31
	s_lshl_b64 s[42:43], s[10:11], 19
	v_readlane_b32 s11, v253, 21
	s_add_u32 s42, s11, s42
	v_readlane_b32 s11, v253, 22
	s_addc_u32 s43, s11, s43
	s_and_b64 s[60:61], s[44:45], exec
	s_cselect_b32 s11, s43, s55
	s_cselect_b32 s73, s42, s54
	s_add_u32 s46, s46, 0x40080
	s_addc_u32 s47, s47, 0
	s_add_u32 s74, s54, 0x100
	s_addc_u32 s75, s55, 0
	s_mov_b32 s78, -2
	s_add_u32 s54, s46, 0xfffc0080
	s_addc_u32 s55, s47, -1
	s_add_i32 s76, 16, 0x10000
	s_cmp_eq_u32 s78, 12
	s_cselect_b32 s61, s15, s55
	s_cselect_b32 s60, s72, s54
	v_add_u32_e32 v80, s76, v146
	s_cselect_b32 s55, s11, s75
	s_cselect_b32 s54, s73, s74
	s_add_i32 s77, 16, 0x14000
	ds_read_b128 v[142:145], v80
	ds_read_b128 v[148:151], v80 offset:1024
	ds_read_b128 v[160:163], v80 offset:2048
	ds_read_b128 v[164:167], v80 offset:3072
	v_add_u32_e32 v80, s77, v146
	ds_read_b128 v[168:171], v80
	ds_read_b128 v[172:175], v80 offset:1024
	ds_read_b128 v[176:179], v80 offset:2048
	ds_read_b128 v[180:183], v80 offset:3072
	v_lshl_add_u64 v[208:209], s[46:47], 0, v[138:139]
	s_add_i32 m0, s13, 0xc000
	ds_read_b128 v[184:187], v147
	ds_read_b128 v[188:191], v147 offset:1024
	ds_read_b128 v[204:207], v147 offset:2048
	ds_read_b128 v[214:217], v147 offset:3072
	ds_read_b128 v[218:221], v147 offset:4096
	ds_read_b128 v[222:225], v147 offset:5120
	ds_read_b128 v[226:229], v147 offset:6144
	ds_read_b128 v[230:233], v147 offset:7168
	global_load_lds_dwordx4 v[208:209], off
	v_lshl_add_u64 v[208:209], s[46:47], 0, v[140:141]
	s_add_i32 m0, s13, 0xe000
	s_nop 0
	global_load_lds_dwordx4 v[208:209], off
	s_waitcnt vmcnt(8)
	s_waitcnt lgkmcnt(0)
	s_barrier
	s_waitcnt lgkmcnt(0)
	v_mfma_f32_16x16x32_bf16 v[118:121], v[142:145], v[184:187], 0
	v_mfma_f32_16x16x32_bf16 v[114:117], v[160:163], v[184:187], 0
	v_mfma_f32_16x16x32_bf16 v[106:109], v[142:145], v[204:207], 0
	v_mfma_f32_16x16x32_bf16 v[98:101], v[160:163], v[204:207], 0
	v_mfma_f32_16x16x32_bf16 v[90:93], v[142:145], v[218:221], 0
	v_mfma_f32_16x16x32_bf16 v[82:85], v[160:163], v[218:221], 0
	v_mfma_f32_16x16x32_bf16 v[68:71], v[142:145], v[226:229], 0
	v_mfma_f32_16x16x32_bf16 v[64:67], v[160:163], v[226:229], 0
	v_mfma_f32_16x16x32_bf16 v[118:121], v[148:151], v[188:191], v[118:121]
	v_mfma_f32_16x16x32_bf16 v[114:117], v[164:167], v[188:191], v[114:117]
	v_mfma_f32_16x16x32_bf16 v[106:109], v[148:151], v[214:217], v[106:109]
	v_mfma_f32_16x16x32_bf16 v[98:101], v[164:167], v[214:217], v[98:101]
	v_mfma_f32_16x16x32_bf16 v[90:93], v[148:151], v[222:225], v[90:93]
	v_mfma_f32_16x16x32_bf16 v[82:85], v[164:167], v[222:225], v[82:85]
	v_mfma_f32_16x16x32_bf16 v[68:71], v[148:151], v[230:233], v[68:71]
	v_mfma_f32_16x16x32_bf16 v[64:67], v[164:167], v[230:233], v[64:67]
	v_mfma_f32_16x16x32_bf16 v[126:129], v[168:171], v[184:187], 0
	v_mfma_f32_16x16x32_bf16 v[122:125], v[176:179], v[184:187], 0
	v_mfma_f32_16x16x32_bf16 v[110:113], v[168:171], v[204:207], 0
	v_mfma_f32_16x16x32_bf16 v[102:105], v[176:179], v[204:207], 0
	v_mfma_f32_16x16x32_bf16 v[94:97], v[168:171], v[218:221], 0
	v_mfma_f32_16x16x32_bf16 v[86:89], v[176:179], v[218:221], 0
	v_mfma_f32_16x16x32_bf16 v[76:79], v[168:171], v[226:229], 0
	v_mfma_f32_16x16x32_bf16 v[72:75], v[176:179], v[226:229], 0
	v_mfma_f32_16x16x32_bf16 v[126:129], v[172:175], v[188:191], v[126:129]
	v_mfma_f32_16x16x32_bf16 v[122:125], v[180:183], v[188:191], v[122:125]
	v_mfma_f32_16x16x32_bf16 v[110:113], v[172:175], v[214:217], v[110:113]
	v_mfma_f32_16x16x32_bf16 v[102:105], v[180:183], v[214:217], v[102:105]
	v_mfma_f32_16x16x32_bf16 v[94:97], v[172:175], v[222:225], v[94:97]
	v_mfma_f32_16x16x32_bf16 v[86:89], v[180:183], v[222:225], v[86:89]
	v_mfma_f32_16x16x32_bf16 v[76:79], v[172:175], v[230:233], v[76:79]
	v_mfma_f32_16x16x32_bf16 v[72:75], v[180:183], v[230:233], v[72:75]
	s_barrier
	s_add_i32 s76, s76, s4
	v_lshl_add_u64 v[208:209], s[54:55], 0, v[134:135]
	s_mov_b32 m0, s76
	ds_read_b128 v[184:187], v147 offset:16384
	ds_read_b128 v[188:191], v147 offset:17408
	ds_read_b128 v[204:207], v147 offset:18432
	ds_read_b128 v[214:217], v147 offset:19456
	ds_read_b128 v[218:221], v147 offset:20480
	ds_read_b128 v[222:225], v147 offset:21504
	ds_read_b128 v[226:229], v147 offset:22528
	ds_read_b128 v[230:233], v147 offset:23552
	global_load_lds_dwordx4 v[208:209], off
	s_add_i32 m0, s76, 0x2000
	s_add_u32 s96, s54, 0x40000
	v_lshl_add_u64 v[234:235], s[54:55], 0, v[130:131]
	s_addc_u32 s97, s55, 0
	s_add_i32 s76, s77, s4
	global_load_lds_dwordx4 v[234:235], off
	v_lshl_add_u64 v[236:237], s[96:97], 0, v[134:135]
	s_mov_b32 m0, s76
	v_lshl_add_u64 v[238:239], s[60:61], 0, v[132:133]
	global_load_lds_dwordx4 v[236:237], off
	v_lshl_add_u64 v[236:237], s[96:97], 0, v[130:131]
	s_add_i32 m0, s76, 0x2000
	s_nop 0
	global_load_lds_dwordx4 v[236:237], off
	v_lshl_add_u64 v[236:237], s[60:61], 0, v[136:137]
	s_mov_b32 m0, s13
	s_nop 0
	global_load_lds_dwordx4 v[236:237], off
	s_mov_b32 m0, s25
	s_nop 0
	global_load_lds_dwordx4 v[238:239], off
	s_waitcnt vmcnt(8)
	s_waitcnt lgkmcnt(0)
	s_barrier
	s_waitcnt lgkmcnt(0)
	v_mfma_f32_16x16x32_bf16 v[52:55], v[142:145], v[184:187], 0
	v_mfma_f32_16x16x32_bf16 v[48:51], v[160:163], v[184:187], 0
	v_mfma_f32_16x16x32_bf16 v[36:39], v[142:145], v[204:207], 0
	v_mfma_f32_16x16x32_bf16 v[32:35], v[160:163], v[204:207], 0
	v_mfma_f32_16x16x32_bf16 v[20:23], v[142:145], v[218:221], 0
	v_mfma_f32_16x16x32_bf16 v[16:19], v[160:163], v[218:221], 0
	v_mfma_f32_16x16x32_bf16 v[8:11], v[142:145], v[226:229], 0
	v_mfma_f32_16x16x32_bf16 v[0:3], v[160:163], v[226:229], 0
	v_mfma_f32_16x16x32_bf16 v[52:55], v[148:151], v[188:191], v[52:55]
	v_mfma_f32_16x16x32_bf16 v[48:51], v[164:167], v[188:191], v[48:51]
	v_mfma_f32_16x16x32_bf16 v[36:39], v[148:151], v[214:217], v[36:39]
	v_mfma_f32_16x16x32_bf16 v[32:35], v[164:167], v[214:217], v[32:35]
	v_mfma_f32_16x16x32_bf16 v[20:23], v[148:151], v[222:225], v[20:23]
	v_mfma_f32_16x16x32_bf16 v[16:19], v[164:167], v[222:225], v[16:19]
	v_mfma_f32_16x16x32_bf16 v[8:11], v[148:151], v[230:233], v[8:11]
	v_mfma_f32_16x16x32_bf16 v[0:3], v[164:167], v[230:233], v[0:3]
	v_mfma_f32_16x16x32_bf16 v[60:63], v[168:171], v[184:187], 0
	v_mfma_f32_16x16x32_bf16 v[56:59], v[176:179], v[184:187], 0
	v_mfma_f32_16x16x32_bf16 v[44:47], v[168:171], v[204:207], 0
	v_mfma_f32_16x16x32_bf16 v[40:43], v[176:179], v[204:207], 0
	v_mfma_f32_16x16x32_bf16 v[28:31], v[168:171], v[218:221], 0
	v_mfma_f32_16x16x32_bf16 v[24:27], v[176:179], v[218:221], 0
	v_mfma_f32_16x16x32_bf16 v[12:15], v[168:171], v[226:229], 0
	v_mfma_f32_16x16x32_bf16 v[4:7], v[176:179], v[226:229], 0
	v_mfma_f32_16x16x32_bf16 v[60:63], v[172:175], v[188:191], v[60:63]
	v_mfma_f32_16x16x32_bf16 v[56:59], v[180:183], v[188:191], v[56:59]
	v_mfma_f32_16x16x32_bf16 v[44:47], v[172:175], v[214:217], v[44:47]
	v_mfma_f32_16x16x32_bf16 v[40:43], v[180:183], v[214:217], v[40:43]
	v_mfma_f32_16x16x32_bf16 v[28:31], v[172:175], v[222:225], v[28:31]
	v_mfma_f32_16x16x32_bf16 v[24:27], v[180:183], v[222:225], v[24:27]
	v_mfma_f32_16x16x32_bf16 v[12:15], v[172:175], v[230:233], v[12:15]
	v_mfma_f32_16x16x32_bf16 v[4:7], v[180:183], v[230:233], v[4:7]
	s_barrier
	s_add_i32 s76, 16, 0x18000
	v_add_u32_e32 v80, s76, v146
	s_add_i32 s77, 16, 0x1c000
	ds_read_b128 v[142:145], v80
	ds_read_b128 v[148:151], v80 offset:1024
	ds_read_b128 v[160:163], v80 offset:2048
	ds_read_b128 v[164:167], v80 offset:3072
	v_add_u32_e32 v80, s77, v146
	ds_read_b128 v[168:171], v80
	ds_read_b128 v[172:175], v80 offset:1024
	ds_read_b128 v[176:179], v80 offset:2048
	ds_read_b128 v[180:183], v80 offset:3072
	s_add_u32 s60, s60, 0x40000
	s_addc_u32 s61, s61, 0
	s_mov_b32 m0, s30
	v_lshl_add_u64 v[240:241], s[60:61], 0, v[136:137]
	ds_read_b128 v[184:187], v147 offset:32768
	ds_read_b128 v[188:191], v147 offset:33792
	ds_read_b128 v[204:207], v147 offset:34816
	ds_read_b128 v[214:217], v147 offset:35840
	ds_read_b128 v[218:221], v147 offset:36864
	ds_read_b128 v[222:225], v147 offset:37888
	ds_read_b128 v[226:229], v147 offset:38912
	ds_read_b128 v[230:233], v147 offset:39936
	global_load_lds_dwordx4 v[240:241], off
	v_lshl_add_u64 v[240:241], s[60:61], 0, v[132:133]
	s_mov_b32 m0, s33
	s_nop 0
	global_load_lds_dwordx4 v[240:241], off
	s_waitcnt vmcnt(8)
	s_waitcnt lgkmcnt(0)
	s_barrier
	s_waitcnt lgkmcnt(0)
	v_mfma_f32_16x16x32_bf16 v[118:121], v[142:145], v[184:187], v[118:121]
	v_mfma_f32_16x16x32_bf16 v[114:117], v[160:163], v[184:187], v[114:117]
	v_mfma_f32_16x16x32_bf16 v[106:109], v[142:145], v[204:207], v[106:109]
	v_mfma_f32_16x16x32_bf16 v[98:101], v[160:163], v[204:207], v[98:101]
	v_mfma_f32_16x16x32_bf16 v[90:93], v[142:145], v[218:221], v[90:93]
	v_mfma_f32_16x16x32_bf16 v[82:85], v[160:163], v[218:221], v[82:85]
	v_mfma_f32_16x16x32_bf16 v[68:71], v[142:145], v[226:229], v[68:71]
	v_mfma_f32_16x16x32_bf16 v[64:67], v[160:163], v[226:229], v[64:67]
	v_mfma_f32_16x16x32_bf16 v[118:121], v[148:151], v[188:191], v[118:121]
	v_mfma_f32_16x16x32_bf16 v[114:117], v[164:167], v[188:191], v[114:117]
	v_mfma_f32_16x16x32_bf16 v[106:109], v[148:151], v[214:217], v[106:109]
	v_mfma_f32_16x16x32_bf16 v[98:101], v[164:167], v[214:217], v[98:101]
	v_mfma_f32_16x16x32_bf16 v[90:93], v[148:151], v[222:225], v[90:93]
	v_mfma_f32_16x16x32_bf16 v[82:85], v[164:167], v[222:225], v[82:85]
	v_mfma_f32_16x16x32_bf16 v[68:71], v[148:151], v[230:233], v[68:71]
	v_mfma_f32_16x16x32_bf16 v[64:67], v[164:167], v[230:233], v[64:67]
	v_mfma_f32_16x16x32_bf16 v[126:129], v[168:171], v[184:187], v[126:129]
	v_mfma_f32_16x16x32_bf16 v[122:125], v[176:179], v[184:187], v[122:125]
	v_mfma_f32_16x16x32_bf16 v[110:113], v[168:171], v[204:207], v[110:113]
	v_mfma_f32_16x16x32_bf16 v[102:105], v[176:179], v[204:207], v[102:105]
	v_mfma_f32_16x16x32_bf16 v[94:97], v[168:171], v[218:221], v[94:97]
	v_mfma_f32_16x16x32_bf16 v[86:89], v[176:179], v[218:221], v[86:89]
	v_mfma_f32_16x16x32_bf16 v[76:79], v[168:171], v[226:229], v[76:79]
	v_mfma_f32_16x16x32_bf16 v[72:75], v[176:179], v[226:229], v[72:75]
	v_mfma_f32_16x16x32_bf16 v[126:129], v[172:175], v[188:191], v[126:129]
	v_mfma_f32_16x16x32_bf16 v[122:125], v[180:183], v[188:191], v[122:125]
	v_mfma_f32_16x16x32_bf16 v[110:113], v[172:175], v[214:217], v[110:113]
	v_mfma_f32_16x16x32_bf16 v[102:105], v[180:183], v[214:217], v[102:105]
	v_mfma_f32_16x16x32_bf16 v[94:97], v[172:175], v[222:225], v[94:97]
	v_mfma_f32_16x16x32_bf16 v[86:89], v[180:183], v[222:225], v[86:89]
	v_mfma_f32_16x16x32_bf16 v[76:79], v[172:175], v[230:233], v[76:79]
	v_mfma_f32_16x16x32_bf16 v[72:75], v[180:183], v[230:233], v[72:75]
	s_barrier
	s_add_i32 s60, s76, s4
	v_lshl_add_u64 v[208:209], v[208:209], 0, s[20:21]
	s_mov_b32 m0, s60
	ds_read_b128 v[184:187], v147 offset:49152
	ds_read_b128 v[188:191], v147 offset:50176
	ds_read_b128 v[204:207], v147 offset:51200
	ds_read_b128 v[214:217], v147 offset:52224
	ds_read_b128 v[218:221], v147 offset:53248
	ds_read_b128 v[222:225], v147 offset:54272
	ds_read_b128 v[226:229], v147 offset:55296
	ds_read_b128 v[230:233], v147 offset:56320
	global_load_lds_dwordx4 v[208:209], off
	s_add_i32 m0, s60, 0x2000
	s_add_u32 s54, s54, 0x40080
	v_lshl_add_u64 v[208:209], v[234:235], 0, s[20:21]
	s_addc_u32 s55, s55, 0
	s_add_i32 s60, s77, s4
	global_load_lds_dwordx4 v[208:209], off
	v_lshl_add_u64 v[208:209], s[54:55], 0, v[134:135]
	s_mov_b32 m0, s60
	s_nop 0
	global_load_lds_dwordx4 v[208:209], off
	v_lshl_add_u64 v[208:209], s[54:55], 0, v[130:131]
	s_add_i32 m0, s60, 0x2000
	s_nop 0
	global_load_lds_dwordx4 v[208:209], off
	v_lshl_add_u64 v[208:209], v[236:237], 0, s[20:21]
	s_mov_b32 m0, s34
	s_nop 0
	global_load_lds_dwordx4 v[208:209], off
	v_lshl_add_u64 v[208:209], v[238:239], 0, s[20:21]
	s_mov_b32 m0, s36
	s_nop 0
	global_load_lds_dwordx4 v[208:209], off
	s_waitcnt vmcnt(8)
	s_waitcnt lgkmcnt(0)
	s_barrier
	s_waitcnt lgkmcnt(0)
	v_mfma_f32_16x16x32_bf16 v[52:55], v[142:145], v[184:187], v[52:55]
	v_mfma_f32_16x16x32_bf16 v[48:51], v[160:163], v[184:187], v[48:51]
	v_mfma_f32_16x16x32_bf16 v[36:39], v[142:145], v[204:207], v[36:39]
	v_mfma_f32_16x16x32_bf16 v[32:35], v[160:163], v[204:207], v[32:35]
	v_mfma_f32_16x16x32_bf16 v[20:23], v[142:145], v[218:221], v[20:23]
	v_mfma_f32_16x16x32_bf16 v[16:19], v[160:163], v[218:221], v[16:19]
	v_mfma_f32_16x16x32_bf16 v[8:11], v[142:145], v[226:229], v[8:11]
	v_mfma_f32_16x16x32_bf16 v[0:3], v[160:163], v[226:229], v[0:3]
	v_mfma_f32_16x16x32_bf16 v[52:55], v[148:151], v[188:191], v[52:55]
	v_mfma_f32_16x16x32_bf16 v[48:51], v[164:167], v[188:191], v[48:51]
	v_mfma_f32_16x16x32_bf16 v[36:39], v[148:151], v[214:217], v[36:39]
	v_mfma_f32_16x16x32_bf16 v[32:35], v[164:167], v[214:217], v[32:35]
	v_mfma_f32_16x16x32_bf16 v[20:23], v[148:151], v[222:225], v[20:23]
	v_mfma_f32_16x16x32_bf16 v[16:19], v[164:167], v[222:225], v[16:19]
	v_mfma_f32_16x16x32_bf16 v[8:11], v[148:151], v[230:233], v[8:11]
	v_mfma_f32_16x16x32_bf16 v[0:3], v[164:167], v[230:233], v[0:3]
	v_mfma_f32_16x16x32_bf16 v[60:63], v[168:171], v[184:187], v[60:63]
	v_mfma_f32_16x16x32_bf16 v[56:59], v[176:179], v[184:187], v[56:59]
	v_mfma_f32_16x16x32_bf16 v[44:47], v[168:171], v[204:207], v[44:47]
	v_mfma_f32_16x16x32_bf16 v[40:43], v[176:179], v[204:207], v[40:43]
	v_mfma_f32_16x16x32_bf16 v[28:31], v[168:171], v[218:221], v[28:31]
	v_mfma_f32_16x16x32_bf16 v[24:27], v[176:179], v[218:221], v[24:27]
	v_mfma_f32_16x16x32_bf16 v[12:15], v[168:171], v[226:229], v[12:15]
	v_mfma_f32_16x16x32_bf16 v[4:7], v[176:179], v[226:229], v[4:7]
	v_mfma_f32_16x16x32_bf16 v[60:63], v[172:175], v[188:191], v[60:63]
	v_mfma_f32_16x16x32_bf16 v[56:59], v[180:183], v[188:191], v[56:59]
	v_mfma_f32_16x16x32_bf16 v[44:47], v[172:175], v[214:217], v[44:47]
	v_mfma_f32_16x16x32_bf16 v[40:43], v[180:183], v[214:217], v[40:43]
	v_mfma_f32_16x16x32_bf16 v[28:31], v[172:175], v[222:225], v[28:31]
	v_mfma_f32_16x16x32_bf16 v[24:27], v[180:183], v[222:225], v[24:27]
	v_mfma_f32_16x16x32_bf16 v[12:15], v[172:175], v[230:233], v[12:15]
	v_mfma_f32_16x16x32_bf16 v[4:7], v[180:183], v[230:233], v[4:7]
	s_barrier
	s_add_i32 s78, s78, 2
	s_add_u32 s46, s46, 0x100
	s_addc_u32 s47, s47, 0
	s_add_u32 s74, s74, 0x100
	s_addc_u32 s75, s75, 0
	s_cmp_gt_u32 s78, 13
	.p2align	6

.LBB0_639:
	s_add_u32 s54, s46, 0x100
	s_addc_u32 s55, s47, 0
	s_mov_b32 s56, -2
	s_waitcnt lgkmcnt(0)
	s_add_u32 s44, s42, 0x100
	s_addc_u32 s45, s43, 0
	s_add_i32 s57, 16, 0x10000
	s_cmp_eq_u32 s56, 40
	s_cselect_b32 s49, s11, s45
	s_cselect_b32 s48, s10, s44
	v_add_u32_e32 v80, s57, v144
	s_cselect_b32 s47, s15, s55
	s_cselect_b32 s46, s14, s54
	s_add_i32 s60, 16, 0x14000
	ds_read_b128 v[146:149], v80
	ds_read_b128 v[160:163], v80 offset:1024
	ds_read_b128 v[164:167], v80 offset:2048
	ds_read_b128 v[168:171], v80 offset:3072
	v_add_u32_e32 v80, s60, v144
	ds_read_b128 v[172:175], v80
	ds_read_b128 v[176:179], v80 offset:1024
	ds_read_b128 v[180:183], v80 offset:2048
	ds_read_b128 v[184:187], v80 offset:3072
	v_lshl_add_u64 v[142:143], s[42:43], 0, v[138:139]
	s_add_i32 m0, s13, 0xc000
	ds_read_b128 v[188:191], v145
	ds_read_b128 v[204:207], v145 offset:1024
	ds_read_b128 v[214:217], v145 offset:2048
	ds_read_b128 v[218:221], v145 offset:3072
	ds_read_b128 v[222:225], v145 offset:4096
	ds_read_b128 v[226:229], v145 offset:5120
	ds_read_b128 v[230:233], v145 offset:6144
	ds_read_b128 v[234:237], v145 offset:7168
	global_load_lds_dwordx4 v[142:143], off
	v_lshl_add_u64 v[142:143], s[42:43], 0, v[140:141]
	s_add_i32 m0, s13, 0xe000
	s_nop 0
	global_load_lds_dwordx4 v[142:143], off
	s_waitcnt vmcnt(8)
	s_waitcnt lgkmcnt(0)
	s_barrier
	s_waitcnt lgkmcnt(0)
	v_mfma_f32_16x16x32_bf16 v[126:129], v[146:149], v[188:191], 0
	v_mfma_f32_16x16x32_bf16 v[122:125], v[164:167], v[188:191], 0
	v_mfma_f32_16x16x32_bf16 v[110:113], v[146:149], v[214:217], 0
	v_mfma_f32_16x16x32_bf16 v[106:109], v[164:167], v[214:217], 0
	v_mfma_f32_16x16x32_bf16 v[94:97], v[146:149], v[222:225], 0
	v_mfma_f32_16x16x32_bf16 v[90:93], v[164:167], v[222:225], 0
	v_mfma_f32_16x16x32_bf16 v[76:79], v[146:149], v[230:233], 0
	v_mfma_f32_16x16x32_bf16 v[72:75], v[164:167], v[230:233], 0
	v_mfma_f32_16x16x32_bf16 v[126:129], v[160:163], v[204:207], v[126:129]
	v_mfma_f32_16x16x32_bf16 v[122:125], v[168:171], v[204:207], v[122:125]
	v_mfma_f32_16x16x32_bf16 v[110:113], v[160:163], v[218:221], v[110:113]
	v_mfma_f32_16x16x32_bf16 v[106:109], v[168:171], v[218:221], v[106:109]
	v_mfma_f32_16x16x32_bf16 v[94:97], v[160:163], v[226:229], v[94:97]
	v_mfma_f32_16x16x32_bf16 v[90:93], v[168:171], v[226:229], v[90:93]
	v_mfma_f32_16x16x32_bf16 v[76:79], v[160:163], v[234:237], v[76:79]
	v_mfma_f32_16x16x32_bf16 v[72:75], v[168:171], v[234:237], v[72:75]
	v_mfma_f32_16x16x32_bf16 v[118:121], v[172:175], v[188:191], 0
	v_mfma_f32_16x16x32_bf16 v[114:117], v[180:183], v[188:191], 0
	v_mfma_f32_16x16x32_bf16 v[102:105], v[172:175], v[214:217], 0
	v_mfma_f32_16x16x32_bf16 v[98:101], v[180:183], v[214:217], 0
	v_mfma_f32_16x16x32_bf16 v[86:89], v[172:175], v[222:225], 0
	v_mfma_f32_16x16x32_bf16 v[82:85], v[180:183], v[222:225], 0
	v_mfma_f32_16x16x32_bf16 v[68:71], v[172:175], v[230:233], 0
	v_mfma_f32_16x16x32_bf16 v[64:67], v[180:183], v[230:233], 0
	v_mfma_f32_16x16x32_bf16 v[118:121], v[176:179], v[204:207], v[118:121]
	v_mfma_f32_16x16x32_bf16 v[114:117], v[184:187], v[204:207], v[114:117]
	v_mfma_f32_16x16x32_bf16 v[102:105], v[176:179], v[218:221], v[102:105]
	v_mfma_f32_16x16x32_bf16 v[98:101], v[184:187], v[218:221], v[98:101]
	v_mfma_f32_16x16x32_bf16 v[86:89], v[176:179], v[226:229], v[86:89]
	v_mfma_f32_16x16x32_bf16 v[82:85], v[184:187], v[226:229], v[82:85]
	v_mfma_f32_16x16x32_bf16 v[68:71], v[176:179], v[234:237], v[68:71]
	v_mfma_f32_16x16x32_bf16 v[64:67], v[184:187], v[234:237], v[64:67]
	s_barrier
	s_add_i32 s42, s57, s4
	v_lshl_add_u64 v[142:143], s[46:47], 0, v[134:135]
	s_mov_b32 m0, s42
	ds_read_b128 v[188:191], v145 offset:16384
	ds_read_b128 v[204:207], v145 offset:17408
	ds_read_b128 v[214:217], v145 offset:18432
	ds_read_b128 v[218:221], v145 offset:19456
	ds_read_b128 v[222:225], v145 offset:20480
	ds_read_b128 v[226:229], v145 offset:21504
	ds_read_b128 v[230:233], v145 offset:22528
	ds_read_b128 v[234:237], v145 offset:23552
	global_load_lds_dwordx4 v[142:143], off
	s_add_i32 m0, s42, 0x2000
	s_add_u32 s42, s46, 0xb0000
	v_lshl_add_u64 v[150:151], s[46:47], 0, v[130:131]
	s_addc_u32 s43, s47, 0
	s_add_i32 s57, s60, s4
	global_load_lds_dwordx4 v[150:151], off
	v_lshl_add_u64 v[208:209], s[42:43], 0, v[134:135]
	s_mov_b32 m0, s57
	v_lshl_add_u64 v[238:239], s[48:49], 0, v[132:133]
	global_load_lds_dwordx4 v[208:209], off
	v_lshl_add_u64 v[208:209], s[42:43], 0, v[130:131]
	s_add_i32 m0, s57, 0x2000
	s_nop 0
	global_load_lds_dwordx4 v[208:209], off
	v_lshl_add_u64 v[208:209], s[48:49], 0, v[136:137]
	s_mov_b32 m0, s13
	s_nop 0
	global_load_lds_dwordx4 v[208:209], off
	s_mov_b32 m0, s25
	s_nop 0
	global_load_lds_dwordx4 v[238:239], off
	s_waitcnt vmcnt(8)
	s_waitcnt lgkmcnt(0)
	s_barrier
	s_waitcnt lgkmcnt(0)
	v_mfma_f32_16x16x32_bf16 v[60:63], v[146:149], v[188:191], 0
	v_mfma_f32_16x16x32_bf16 v[56:59], v[164:167], v[188:191], 0
	v_mfma_f32_16x16x32_bf16 v[44:47], v[146:149], v[214:217], 0
	v_mfma_f32_16x16x32_bf16 v[40:43], v[164:167], v[214:217], 0
	v_mfma_f32_16x16x32_bf16 v[28:31], v[146:149], v[222:225], 0
	v_mfma_f32_16x16x32_bf16 v[24:27], v[164:167], v[222:225], 0
	v_mfma_f32_16x16x32_bf16 v[12:15], v[146:149], v[230:233], 0
	v_mfma_f32_16x16x32_bf16 v[8:11], v[164:167], v[230:233], 0
	v_mfma_f32_16x16x32_bf16 v[60:63], v[160:163], v[204:207], v[60:63]
	v_mfma_f32_16x16x32_bf16 v[56:59], v[168:171], v[204:207], v[56:59]
	v_mfma_f32_16x16x32_bf16 v[44:47], v[160:163], v[218:221], v[44:47]
	v_mfma_f32_16x16x32_bf16 v[40:43], v[168:171], v[218:221], v[40:43]
	v_mfma_f32_16x16x32_bf16 v[28:31], v[160:163], v[226:229], v[28:31]
	v_mfma_f32_16x16x32_bf16 v[24:27], v[168:171], v[226:229], v[24:27]
	v_mfma_f32_16x16x32_bf16 v[12:15], v[160:163], v[234:237], v[12:15]
	v_mfma_f32_16x16x32_bf16 v[8:11], v[168:171], v[234:237], v[8:11]
	v_mfma_f32_16x16x32_bf16 v[52:55], v[172:175], v[188:191], 0
	v_mfma_f32_16x16x32_bf16 v[48:51], v[180:183], v[188:191], 0
	v_mfma_f32_16x16x32_bf16 v[36:39], v[172:175], v[214:217], 0
	v_mfma_f32_16x16x32_bf16 v[32:35], v[180:183], v[214:217], 0
	v_mfma_f32_16x16x32_bf16 v[20:23], v[172:175], v[222:225], 0
	v_mfma_f32_16x16x32_bf16 v[16:19], v[180:183], v[222:225], 0
	v_mfma_f32_16x16x32_bf16 v[4:7], v[172:175], v[230:233], 0
	v_mfma_f32_16x16x32_bf16 v[0:3], v[180:183], v[230:233], 0
	v_mfma_f32_16x16x32_bf16 v[52:55], v[176:179], v[204:207], v[52:55]
	v_mfma_f32_16x16x32_bf16 v[48:51], v[184:187], v[204:207], v[48:51]
	v_mfma_f32_16x16x32_bf16 v[36:39], v[176:179], v[218:221], v[36:39]
	v_mfma_f32_16x16x32_bf16 v[32:35], v[184:187], v[218:221], v[32:35]
	v_mfma_f32_16x16x32_bf16 v[20:23], v[176:179], v[226:229], v[20:23]
	v_mfma_f32_16x16x32_bf16 v[16:19], v[184:187], v[226:229], v[16:19]
	v_mfma_f32_16x16x32_bf16 v[4:7], v[176:179], v[234:237], v[4:7]
	v_mfma_f32_16x16x32_bf16 v[0:3], v[184:187], v[234:237], v[0:3]
	s_barrier
	s_add_i32 s57, 16, 0x18000
	v_add_u32_e32 v80, s57, v144
	s_add_i32 s60, 16, 0x1c000
	ds_read_b128 v[146:149], v80
	ds_read_b128 v[160:163], v80 offset:1024
	ds_read_b128 v[164:167], v80 offset:2048
	ds_read_b128 v[168:171], v80 offset:3072
	v_add_u32_e32 v80, s60, v144
	ds_read_b128 v[172:175], v80
	ds_read_b128 v[176:179], v80 offset:1024
	ds_read_b128 v[180:183], v80 offset:2048
	ds_read_b128 v[184:187], v80 offset:3072
	s_add_u32 s42, s48, 0xb0000
	s_addc_u32 s43, s49, 0
	s_mov_b32 m0, s30
	v_lshl_add_u64 v[240:241], s[42:43], 0, v[136:137]
	ds_read_b128 v[188:191], v145 offset:32768
	ds_read_b128 v[204:207], v145 offset:33792
	ds_read_b128 v[214:217], v145 offset:34816
	ds_read_b128 v[218:221], v145 offset:35840
	ds_read_b128 v[222:225], v145 offset:36864
	ds_read_b128 v[226:229], v145 offset:37888
	ds_read_b128 v[230:233], v145 offset:38912
	ds_read_b128 v[234:237], v145 offset:39936
	global_load_lds_dwordx4 v[240:241], off
	v_lshl_add_u64 v[240:241], s[42:43], 0, v[132:133]
	s_mov_b32 m0, s33
	s_nop 0
	global_load_lds_dwordx4 v[240:241], off
	s_waitcnt vmcnt(8)
	s_waitcnt lgkmcnt(0)
	s_barrier
	s_waitcnt lgkmcnt(0)
	v_mfma_f32_16x16x32_bf16 v[126:129], v[146:149], v[188:191], v[126:129]
	v_mfma_f32_16x16x32_bf16 v[122:125], v[164:167], v[188:191], v[122:125]
	v_mfma_f32_16x16x32_bf16 v[110:113], v[146:149], v[214:217], v[110:113]
	v_mfma_f32_16x16x32_bf16 v[106:109], v[164:167], v[214:217], v[106:109]
	v_mfma_f32_16x16x32_bf16 v[94:97], v[146:149], v[222:225], v[94:97]
	v_mfma_f32_16x16x32_bf16 v[90:93], v[164:167], v[222:225], v[90:93]
	v_mfma_f32_16x16x32_bf16 v[76:79], v[146:149], v[230:233], v[76:79]
	v_mfma_f32_16x16x32_bf16 v[72:75], v[164:167], v[230:233], v[72:75]
	v_mfma_f32_16x16x32_bf16 v[126:129], v[160:163], v[204:207], v[126:129]
	v_mfma_f32_16x16x32_bf16 v[122:125], v[168:171], v[204:207], v[122:125]
	v_mfma_f32_16x16x32_bf16 v[110:113], v[160:163], v[218:221], v[110:113]
	v_mfma_f32_16x16x32_bf16 v[106:109], v[168:171], v[218:221], v[106:109]
	v_mfma_f32_16x16x32_bf16 v[94:97], v[160:163], v[226:229], v[94:97]
	v_mfma_f32_16x16x32_bf16 v[90:93], v[168:171], v[226:229], v[90:93]
	v_mfma_f32_16x16x32_bf16 v[76:79], v[160:163], v[234:237], v[76:79]
	v_mfma_f32_16x16x32_bf16 v[72:75], v[168:171], v[234:237], v[72:75]
	v_mfma_f32_16x16x32_bf16 v[118:121], v[172:175], v[188:191], v[118:121]
	v_mfma_f32_16x16x32_bf16 v[114:117], v[180:183], v[188:191], v[114:117]
	v_mfma_f32_16x16x32_bf16 v[102:105], v[172:175], v[214:217], v[102:105]
	v_mfma_f32_16x16x32_bf16 v[98:101], v[180:183], v[214:217], v[98:101]
	v_mfma_f32_16x16x32_bf16 v[86:89], v[172:175], v[222:225], v[86:89]
	v_mfma_f32_16x16x32_bf16 v[82:85], v[180:183], v[222:225], v[82:85]
	v_mfma_f32_16x16x32_bf16 v[68:71], v[172:175], v[230:233], v[68:71]
	v_mfma_f32_16x16x32_bf16 v[64:67], v[180:183], v[230:233], v[64:67]
	v_mfma_f32_16x16x32_bf16 v[118:121], v[176:179], v[204:207], v[118:121]
	v_mfma_f32_16x16x32_bf16 v[114:117], v[184:187], v[204:207], v[114:117]
	v_mfma_f32_16x16x32_bf16 v[102:105], v[176:179], v[218:221], v[102:105]
	v_mfma_f32_16x16x32_bf16 v[98:101], v[184:187], v[218:221], v[98:101]
	v_mfma_f32_16x16x32_bf16 v[86:89], v[176:179], v[226:229], v[86:89]
	v_mfma_f32_16x16x32_bf16 v[82:85], v[184:187], v[226:229], v[82:85]
	v_mfma_f32_16x16x32_bf16 v[68:71], v[176:179], v[234:237], v[68:71]
	v_mfma_f32_16x16x32_bf16 v[64:67], v[184:187], v[234:237], v[64:67]
	s_barrier
	s_add_i32 s42, s57, s4
	v_lshl_add_u64 v[142:143], v[142:143], 0, s[20:21]
	s_mov_b32 m0, s42
	ds_read_b128 v[188:191], v145 offset:49152
	ds_read_b128 v[204:207], v145 offset:50176
	ds_read_b128 v[214:217], v145 offset:51200
	ds_read_b128 v[218:221], v145 offset:52224
	ds_read_b128 v[222:225], v145 offset:53248
	ds_read_b128 v[226:229], v145 offset:54272
	ds_read_b128 v[230:233], v145 offset:55296
	ds_read_b128 v[234:237], v145 offset:56320
	global_load_lds_dwordx4 v[142:143], off
	s_add_i32 m0, s42, 0x2000
	s_add_u32 s42, s46, 0xb0080
	v_lshl_add_u64 v[142:143], v[150:151], 0, s[20:21]
	s_addc_u32 s43, s47, 0
	s_add_i32 s46, s60, s4
	global_load_lds_dwordx4 v[142:143], off
	v_lshl_add_u64 v[142:143], s[42:43], 0, v[134:135]
	s_mov_b32 m0, s46
	s_nop 0
	global_load_lds_dwordx4 v[142:143], off
	v_lshl_add_u64 v[142:143], s[42:43], 0, v[130:131]
	s_add_i32 m0, s46, 0x2000
	s_nop 0
	global_load_lds_dwordx4 v[142:143], off
	v_lshl_add_u64 v[142:143], v[208:209], 0, s[20:21]
	s_mov_b32 m0, s34
	s_nop 0
	global_load_lds_dwordx4 v[142:143], off
	v_lshl_add_u64 v[142:143], v[238:239], 0, s[20:21]
	s_mov_b32 m0, s36
	s_nop 0
	global_load_lds_dwordx4 v[142:143], off
	s_waitcnt vmcnt(8)
	s_waitcnt lgkmcnt(0)
	s_barrier
	s_waitcnt lgkmcnt(0)
	v_mfma_f32_16x16x32_bf16 v[60:63], v[146:149], v[188:191], v[60:63]
	v_mfma_f32_16x16x32_bf16 v[56:59], v[164:167], v[188:191], v[56:59]
	v_mfma_f32_16x16x32_bf16 v[44:47], v[146:149], v[214:217], v[44:47]
	v_mfma_f32_16x16x32_bf16 v[40:43], v[164:167], v[214:217], v[40:43]
	v_mfma_f32_16x16x32_bf16 v[28:31], v[146:149], v[222:225], v[28:31]
	v_mfma_f32_16x16x32_bf16 v[24:27], v[164:167], v[222:225], v[24:27]
	v_mfma_f32_16x16x32_bf16 v[12:15], v[146:149], v[230:233], v[12:15]
	v_mfma_f32_16x16x32_bf16 v[8:11], v[164:167], v[230:233], v[8:11]
	v_mfma_f32_16x16x32_bf16 v[60:63], v[160:163], v[204:207], v[60:63]
	v_mfma_f32_16x16x32_bf16 v[56:59], v[168:171], v[204:207], v[56:59]
	v_mfma_f32_16x16x32_bf16 v[44:47], v[160:163], v[218:221], v[44:47]
	v_mfma_f32_16x16x32_bf16 v[40:43], v[168:171], v[218:221], v[40:43]
	v_mfma_f32_16x16x32_bf16 v[28:31], v[160:163], v[226:229], v[28:31]
	v_mfma_f32_16x16x32_bf16 v[24:27], v[168:171], v[226:229], v[24:27]
	v_mfma_f32_16x16x32_bf16 v[12:15], v[160:163], v[234:237], v[12:15]
	v_mfma_f32_16x16x32_bf16 v[8:11], v[168:171], v[234:237], v[8:11]
	v_mfma_f32_16x16x32_bf16 v[52:55], v[172:175], v[188:191], v[52:55]
	v_mfma_f32_16x16x32_bf16 v[48:51], v[180:183], v[188:191], v[48:51]
	v_mfma_f32_16x16x32_bf16 v[36:39], v[172:175], v[214:217], v[36:39]
	v_mfma_f32_16x16x32_bf16 v[32:35], v[180:183], v[214:217], v[32:35]
	v_mfma_f32_16x16x32_bf16 v[20:23], v[172:175], v[222:225], v[20:23]
	v_mfma_f32_16x16x32_bf16 v[16:19], v[180:183], v[222:225], v[16:19]
	v_mfma_f32_16x16x32_bf16 v[4:7], v[172:175], v[230:233], v[4:7]
	v_mfma_f32_16x16x32_bf16 v[0:3], v[180:183], v[230:233], v[0:3]
	v_mfma_f32_16x16x32_bf16 v[52:55], v[176:179], v[204:207], v[52:55]
	v_mfma_f32_16x16x32_bf16 v[48:51], v[184:187], v[204:207], v[48:51]
	v_mfma_f32_16x16x32_bf16 v[36:39], v[176:179], v[218:221], v[36:39]
	v_mfma_f32_16x16x32_bf16 v[32:35], v[184:187], v[218:221], v[32:35]
	v_mfma_f32_16x16x32_bf16 v[20:23], v[176:179], v[226:229], v[20:23]
	v_mfma_f32_16x16x32_bf16 v[16:19], v[184:187], v[226:229], v[16:19]
	v_mfma_f32_16x16x32_bf16 v[4:7], v[176:179], v[234:237], v[4:7]
	v_mfma_f32_16x16x32_bf16 v[0:3], v[184:187], v[234:237], v[0:3]
	s_barrier
	s_add_i32 s56, s56, 2
	s_add_u32 s54, s54, 0x100
	s_addc_u32 s55, s55, 0
	s_cmp_gt_u32 s56, 41
	s_mov_b64 s[42:43], s[44:45]
	.p2align	6

.LBB0_676:
	s_ashr_i32 s15, s14, 31
	s_lshl_b64 s[42:43], s[14:15], 19
	s_add_u32 s42, s38, s42
	s_addc_u32 s43, s39, s43
	s_and_b64 s[44:45], s[40:41], exec
	s_cselect_b32 s15, s43, s47
	s_cselect_b32 s54, s42, s46
	s_ashr_i32 s11, s10, 31
	s_lshl_b64 s[44:45], s[10:11], 19
	v_readlane_b32 s11, v253, 33
	s_add_u32 s44, s11, s44
	v_readlane_b32 s11, v253, 34
	s_addc_u32 s45, s11, s45
	s_and_b64 s[50:51], s[40:41], exec
	s_cselect_b32 s11, s45, s49
	s_cselect_b32 s55, s44, s48
	s_add_u32 s46, s46, 0x40080
	s_addc_u32 s47, s47, 0
	s_add_u32 s56, s48, 0x100
	s_addc_u32 s57, s49, 0
	s_mov_b32 s60, -2
	s_add_u32 s48, s46, 0xfffc0080
	s_addc_u32 s49, s47, -1
	s_add_i32 s61, 16, 0x10000
	s_cmp_eq_u32 s60, 12
	s_cselect_b32 s51, s15, s49
	s_cselect_b32 s50, s54, s48
	v_add_u32_e32 v80, s61, v146
	s_cselect_b32 s49, s11, s57
	s_cselect_b32 s48, s55, s56
	s_add_i32 s74, 16, 0x14000
	ds_read_b128 v[142:145], v80
	ds_read_b128 v[148:151], v80 offset:1024
	ds_read_b128 v[160:163], v80 offset:2048
	ds_read_b128 v[164:167], v80 offset:3072
	v_add_u32_e32 v80, s74, v146
	ds_read_b128 v[168:171], v80
	ds_read_b128 v[172:175], v80 offset:1024
	ds_read_b128 v[176:179], v80 offset:2048
	ds_read_b128 v[180:183], v80 offset:3072
	v_lshl_add_u64 v[208:209], s[46:47], 0, v[138:139]
	s_add_i32 m0, s13, 0xc000
	ds_read_b128 v[184:187], v147
	ds_read_b128 v[188:191], v147 offset:1024
	ds_read_b128 v[204:207], v147 offset:2048
	ds_read_b128 v[214:217], v147 offset:3072
	ds_read_b128 v[218:221], v147 offset:4096
	ds_read_b128 v[222:225], v147 offset:5120
	ds_read_b128 v[226:229], v147 offset:6144
	ds_read_b128 v[230:233], v147 offset:7168
	global_load_lds_dwordx4 v[208:209], off
	v_lshl_add_u64 v[208:209], s[46:47], 0, v[140:141]
	s_add_i32 m0, s13, 0xe000
	s_nop 0
	global_load_lds_dwordx4 v[208:209], off
	s_waitcnt vmcnt(8)
	s_waitcnt lgkmcnt(0)
	s_barrier
	s_waitcnt lgkmcnt(0)
	v_mfma_f32_16x16x32_bf16 v[126:129], v[142:145], v[184:187], 0
	v_mfma_f32_16x16x32_bf16 v[118:121], v[160:163], v[184:187], 0
	v_mfma_f32_16x16x32_bf16 v[110:113], v[142:145], v[204:207], 0
	v_mfma_f32_16x16x32_bf16 v[102:105], v[160:163], v[204:207], 0
	v_mfma_f32_16x16x32_bf16 v[94:97], v[142:145], v[218:221], 0
	v_mfma_f32_16x16x32_bf16 v[86:89], v[160:163], v[218:221], 0
	v_mfma_f32_16x16x32_bf16 v[76:79], v[142:145], v[226:229], 0
	v_mfma_f32_16x16x32_bf16 v[68:71], v[160:163], v[226:229], 0
	v_mfma_f32_16x16x32_bf16 v[126:129], v[148:151], v[188:191], v[126:129]
	v_mfma_f32_16x16x32_bf16 v[118:121], v[164:167], v[188:191], v[118:121]
	v_mfma_f32_16x16x32_bf16 v[110:113], v[148:151], v[214:217], v[110:113]
	v_mfma_f32_16x16x32_bf16 v[102:105], v[164:167], v[214:217], v[102:105]
	v_mfma_f32_16x16x32_bf16 v[94:97], v[148:151], v[222:225], v[94:97]
	v_mfma_f32_16x16x32_bf16 v[86:89], v[164:167], v[222:225], v[86:89]
	v_mfma_f32_16x16x32_bf16 v[76:79], v[148:151], v[230:233], v[76:79]
	v_mfma_f32_16x16x32_bf16 v[68:71], v[164:167], v[230:233], v[68:71]
	v_mfma_f32_16x16x32_bf16 v[122:125], v[168:171], v[184:187], 0
	v_mfma_f32_16x16x32_bf16 v[114:117], v[176:179], v[184:187], 0
	v_mfma_f32_16x16x32_bf16 v[106:109], v[168:171], v[204:207], 0
	v_mfma_f32_16x16x32_bf16 v[98:101], v[176:179], v[204:207], 0
	v_mfma_f32_16x16x32_bf16 v[90:93], v[168:171], v[218:221], 0
	v_mfma_f32_16x16x32_bf16 v[82:85], v[176:179], v[218:221], 0
	v_mfma_f32_16x16x32_bf16 v[72:75], v[168:171], v[226:229], 0
	v_mfma_f32_16x16x32_bf16 v[64:67], v[176:179], v[226:229], 0
	v_mfma_f32_16x16x32_bf16 v[122:125], v[172:175], v[188:191], v[122:125]
	v_mfma_f32_16x16x32_bf16 v[114:117], v[180:183], v[188:191], v[114:117]
	v_mfma_f32_16x16x32_bf16 v[106:109], v[172:175], v[214:217], v[106:109]
	v_mfma_f32_16x16x32_bf16 v[98:101], v[180:183], v[214:217], v[98:101]
	v_mfma_f32_16x16x32_bf16 v[90:93], v[172:175], v[222:225], v[90:93]
	v_mfma_f32_16x16x32_bf16 v[82:85], v[180:183], v[222:225], v[82:85]
	v_mfma_f32_16x16x32_bf16 v[72:75], v[172:175], v[230:233], v[72:75]
	v_mfma_f32_16x16x32_bf16 v[64:67], v[180:183], v[230:233], v[64:67]
	s_barrier
	s_add_i32 s61, s61, s4
	v_lshl_add_u64 v[208:209], s[48:49], 0, v[134:135]
	s_mov_b32 m0, s61
	ds_read_b128 v[184:187], v147 offset:16384
	ds_read_b128 v[188:191], v147 offset:17408
	ds_read_b128 v[204:207], v147 offset:18432
	ds_read_b128 v[214:217], v147 offset:19456
	ds_read_b128 v[218:221], v147 offset:20480
	ds_read_b128 v[222:225], v147 offset:21504
	ds_read_b128 v[226:229], v147 offset:22528
	ds_read_b128 v[230:233], v147 offset:23552
	global_load_lds_dwordx4 v[208:209], off
	s_add_i32 m0, s61, 0x2000
	s_add_u32 s66, s48, 0x40000
	v_lshl_add_u64 v[234:235], s[48:49], 0, v[130:131]
	s_addc_u32 s67, s49, 0
	s_add_i32 s61, s74, s4
	global_load_lds_dwordx4 v[234:235], off
	v_lshl_add_u64 v[236:237], s[66:67], 0, v[134:135]
	s_mov_b32 m0, s61
	v_lshl_add_u64 v[238:239], s[50:51], 0, v[132:133]
	global_load_lds_dwordx4 v[236:237], off
	v_lshl_add_u64 v[236:237], s[66:67], 0, v[130:131]
	s_add_i32 m0, s61, 0x2000
	s_nop 0
	global_load_lds_dwordx4 v[236:237], off
	v_lshl_add_u64 v[236:237], s[50:51], 0, v[136:137]
	s_mov_b32 m0, s13
	s_nop 0
	global_load_lds_dwordx4 v[236:237], off
	s_mov_b32 m0, s25
	s_nop 0
	global_load_lds_dwordx4 v[238:239], off
	s_waitcnt vmcnt(8)
	s_waitcnt lgkmcnt(0)
	s_barrier
	s_waitcnt lgkmcnt(0)
	v_mfma_f32_16x16x32_bf16 v[60:63], v[142:145], v[184:187], 0
	v_mfma_f32_16x16x32_bf16 v[52:55], v[160:163], v[184:187], 0
	v_mfma_f32_16x16x32_bf16 v[44:47], v[142:145], v[204:207], 0
	v_mfma_f32_16x16x32_bf16 v[36:39], v[160:163], v[204:207], 0
	v_mfma_f32_16x16x32_bf16 v[28:31], v[142:145], v[218:221], 0
	v_mfma_f32_16x16x32_bf16 v[20:23], v[160:163], v[218:221], 0
	v_mfma_f32_16x16x32_bf16 v[12:15], v[142:145], v[226:229], 0
	v_mfma_f32_16x16x32_bf16 v[4:7], v[160:163], v[226:229], 0
	v_mfma_f32_16x16x32_bf16 v[60:63], v[148:151], v[188:191], v[60:63]
	v_mfma_f32_16x16x32_bf16 v[52:55], v[164:167], v[188:191], v[52:55]
	v_mfma_f32_16x16x32_bf16 v[44:47], v[148:151], v[214:217], v[44:47]
	v_mfma_f32_16x16x32_bf16 v[36:39], v[164:167], v[214:217], v[36:39]
	v_mfma_f32_16x16x32_bf16 v[28:31], v[148:151], v[222:225], v[28:31]
	v_mfma_f32_16x16x32_bf16 v[20:23], v[164:167], v[222:225], v[20:23]
	v_mfma_f32_16x16x32_bf16 v[12:15], v[148:151], v[230:233], v[12:15]
	v_mfma_f32_16x16x32_bf16 v[4:7], v[164:167], v[230:233], v[4:7]
	v_mfma_f32_16x16x32_bf16 v[56:59], v[168:171], v[184:187], 0
	v_mfma_f32_16x16x32_bf16 v[48:51], v[176:179], v[184:187], 0
	v_mfma_f32_16x16x32_bf16 v[40:43], v[168:171], v[204:207], 0
	v_mfma_f32_16x16x32_bf16 v[32:35], v[176:179], v[204:207], 0
	v_mfma_f32_16x16x32_bf16 v[24:27], v[168:171], v[218:221], 0
	v_mfma_f32_16x16x32_bf16 v[16:19], v[176:179], v[218:221], 0
	v_mfma_f32_16x16x32_bf16 v[8:11], v[168:171], v[226:229], 0
	v_mfma_f32_16x16x32_bf16 v[0:3], v[176:179], v[226:229], 0
	v_mfma_f32_16x16x32_bf16 v[56:59], v[172:175], v[188:191], v[56:59]
	v_mfma_f32_16x16x32_bf16 v[48:51], v[180:183], v[188:191], v[48:51]
	v_mfma_f32_16x16x32_bf16 v[40:43], v[172:175], v[214:217], v[40:43]
	v_mfma_f32_16x16x32_bf16 v[32:35], v[180:183], v[214:217], v[32:35]
	v_mfma_f32_16x16x32_bf16 v[24:27], v[172:175], v[222:225], v[24:27]
	v_mfma_f32_16x16x32_bf16 v[16:19], v[180:183], v[222:225], v[16:19]
	v_mfma_f32_16x16x32_bf16 v[8:11], v[172:175], v[230:233], v[8:11]
	v_mfma_f32_16x16x32_bf16 v[0:3], v[180:183], v[230:233], v[0:3]
	s_barrier
	s_add_i32 s61, 16, 0x18000
	v_add_u32_e32 v80, s61, v146
	s_add_i32 s66, 16, 0x1c000
	ds_read_b128 v[142:145], v80
	ds_read_b128 v[148:151], v80 offset:1024
	ds_read_b128 v[160:163], v80 offset:2048
	ds_read_b128 v[164:167], v80 offset:3072
	v_add_u32_e32 v80, s66, v146
	ds_read_b128 v[168:171], v80
	ds_read_b128 v[172:175], v80 offset:1024
	ds_read_b128 v[176:179], v80 offset:2048
	ds_read_b128 v[180:183], v80 offset:3072
	s_add_u32 s50, s50, 0x40000
	s_addc_u32 s51, s51, 0
	s_mov_b32 m0, s30
	v_lshl_add_u64 v[240:241], s[50:51], 0, v[136:137]
	ds_read_b128 v[184:187], v147 offset:32768
	ds_read_b128 v[188:191], v147 offset:33792
	ds_read_b128 v[204:207], v147 offset:34816
	ds_read_b128 v[214:217], v147 offset:35840
	ds_read_b128 v[218:221], v147 offset:36864
	ds_read_b128 v[222:225], v147 offset:37888
	ds_read_b128 v[226:229], v147 offset:38912
	ds_read_b128 v[230:233], v147 offset:39936
	global_load_lds_dwordx4 v[240:241], off
	v_lshl_add_u64 v[240:241], s[50:51], 0, v[132:133]
	s_mov_b32 m0, s33
	s_nop 0
	global_load_lds_dwordx4 v[240:241], off
	s_waitcnt vmcnt(8)
	s_waitcnt lgkmcnt(0)
	s_barrier
	s_waitcnt lgkmcnt(0)
	v_mfma_f32_16x16x32_bf16 v[126:129], v[142:145], v[184:187], v[126:129]
	v_mfma_f32_16x16x32_bf16 v[118:121], v[160:163], v[184:187], v[118:121]
	v_mfma_f32_16x16x32_bf16 v[110:113], v[142:145], v[204:207], v[110:113]
	v_mfma_f32_16x16x32_bf16 v[102:105], v[160:163], v[204:207], v[102:105]
	v_mfma_f32_16x16x32_bf16 v[94:97], v[142:145], v[218:221], v[94:97]
	v_mfma_f32_16x16x32_bf16 v[86:89], v[160:163], v[218:221], v[86:89]
	v_mfma_f32_16x16x32_bf16 v[76:79], v[142:145], v[226:229], v[76:79]
	v_mfma_f32_16x16x32_bf16 v[68:71], v[160:163], v[226:229], v[68:71]
	v_mfma_f32_16x16x32_bf16 v[126:129], v[148:151], v[188:191], v[126:129]
	v_mfma_f32_16x16x32_bf16 v[118:121], v[164:167], v[188:191], v[118:121]
	v_mfma_f32_16x16x32_bf16 v[110:113], v[148:151], v[214:217], v[110:113]
	v_mfma_f32_16x16x32_bf16 v[102:105], v[164:167], v[214:217], v[102:105]
	v_mfma_f32_16x16x32_bf16 v[94:97], v[148:151], v[222:225], v[94:97]
	v_mfma_f32_16x16x32_bf16 v[86:89], v[164:167], v[222:225], v[86:89]
	v_mfma_f32_16x16x32_bf16 v[76:79], v[148:151], v[230:233], v[76:79]
	v_mfma_f32_16x16x32_bf16 v[68:71], v[164:167], v[230:233], v[68:71]
	v_mfma_f32_16x16x32_bf16 v[122:125], v[168:171], v[184:187], v[122:125]
	v_mfma_f32_16x16x32_bf16 v[114:117], v[176:179], v[184:187], v[114:117]
	v_mfma_f32_16x16x32_bf16 v[106:109], v[168:171], v[204:207], v[106:109]
	v_mfma_f32_16x16x32_bf16 v[98:101], v[176:179], v[204:207], v[98:101]
	v_mfma_f32_16x16x32_bf16 v[90:93], v[168:171], v[218:221], v[90:93]
	v_mfma_f32_16x16x32_bf16 v[82:85], v[176:179], v[218:221], v[82:85]
	v_mfma_f32_16x16x32_bf16 v[72:75], v[168:171], v[226:229], v[72:75]
	v_mfma_f32_16x16x32_bf16 v[64:67], v[176:179], v[226:229], v[64:67]
	v_mfma_f32_16x16x32_bf16 v[122:125], v[172:175], v[188:191], v[122:125]
	v_mfma_f32_16x16x32_bf16 v[114:117], v[180:183], v[188:191], v[114:117]
	v_mfma_f32_16x16x32_bf16 v[106:109], v[172:175], v[214:217], v[106:109]
	v_mfma_f32_16x16x32_bf16 v[98:101], v[180:183], v[214:217], v[98:101]
	v_mfma_f32_16x16x32_bf16 v[90:93], v[172:175], v[222:225], v[90:93]
	v_mfma_f32_16x16x32_bf16 v[82:85], v[180:183], v[222:225], v[82:85]
	v_mfma_f32_16x16x32_bf16 v[72:75], v[172:175], v[230:233], v[72:75]
	v_mfma_f32_16x16x32_bf16 v[64:67], v[180:183], v[230:233], v[64:67]
	s_barrier
	s_add_i32 s50, s61, s4
	v_lshl_add_u64 v[208:209], v[208:209], 0, s[20:21]
	s_mov_b32 m0, s50
	ds_read_b128 v[184:187], v147 offset:49152
	ds_read_b128 v[188:191], v147 offset:50176
	ds_read_b128 v[204:207], v147 offset:51200
	ds_read_b128 v[214:217], v147 offset:52224
	ds_read_b128 v[218:221], v147 offset:53248
	ds_read_b128 v[222:225], v147 offset:54272
	ds_read_b128 v[226:229], v147 offset:55296
	ds_read_b128 v[230:233], v147 offset:56320
	global_load_lds_dwordx4 v[208:209], off
	s_add_i32 m0, s50, 0x2000
	s_add_u32 s48, s48, 0x40080
	v_lshl_add_u64 v[208:209], v[234:235], 0, s[20:21]
	s_addc_u32 s49, s49, 0
	s_add_i32 s50, s66, s4
	global_load_lds_dwordx4 v[208:209], off
	v_lshl_add_u64 v[208:209], s[48:49], 0, v[134:135]
	s_mov_b32 m0, s50
	s_nop 0
	global_load_lds_dwordx4 v[208:209], off
	v_lshl_add_u64 v[208:209], s[48:49], 0, v[130:131]
	s_add_i32 m0, s50, 0x2000
	s_nop 0
	global_load_lds_dwordx4 v[208:209], off
	v_lshl_add_u64 v[208:209], v[236:237], 0, s[20:21]
	s_mov_b32 m0, s34
	s_nop 0
	global_load_lds_dwordx4 v[208:209], off
	v_lshl_add_u64 v[208:209], v[238:239], 0, s[20:21]
	s_mov_b32 m0, s36
	s_nop 0
	global_load_lds_dwordx4 v[208:209], off
	s_waitcnt vmcnt(8)
	s_waitcnt lgkmcnt(0)
	s_barrier
	s_waitcnt lgkmcnt(0)
	v_mfma_f32_16x16x32_bf16 v[60:63], v[142:145], v[184:187], v[60:63]
	v_mfma_f32_16x16x32_bf16 v[52:55], v[160:163], v[184:187], v[52:55]
	v_mfma_f32_16x16x32_bf16 v[44:47], v[142:145], v[204:207], v[44:47]
	v_mfma_f32_16x16x32_bf16 v[36:39], v[160:163], v[204:207], v[36:39]
	v_mfma_f32_16x16x32_bf16 v[28:31], v[142:145], v[218:221], v[28:31]
	v_mfma_f32_16x16x32_bf16 v[20:23], v[160:163], v[218:221], v[20:23]
	v_mfma_f32_16x16x32_bf16 v[12:15], v[142:145], v[226:229], v[12:15]
	v_mfma_f32_16x16x32_bf16 v[4:7], v[160:163], v[226:229], v[4:7]
	v_mfma_f32_16x16x32_bf16 v[60:63], v[148:151], v[188:191], v[60:63]
	v_mfma_f32_16x16x32_bf16 v[52:55], v[164:167], v[188:191], v[52:55]
	v_mfma_f32_16x16x32_bf16 v[44:47], v[148:151], v[214:217], v[44:47]
	v_mfma_f32_16x16x32_bf16 v[36:39], v[164:167], v[214:217], v[36:39]
	v_mfma_f32_16x16x32_bf16 v[28:31], v[148:151], v[222:225], v[28:31]
	v_mfma_f32_16x16x32_bf16 v[20:23], v[164:167], v[222:225], v[20:23]
	v_mfma_f32_16x16x32_bf16 v[12:15], v[148:151], v[230:233], v[12:15]
	v_mfma_f32_16x16x32_bf16 v[4:7], v[164:167], v[230:233], v[4:7]
	v_mfma_f32_16x16x32_bf16 v[56:59], v[168:171], v[184:187], v[56:59]
	v_mfma_f32_16x16x32_bf16 v[48:51], v[176:179], v[184:187], v[48:51]
	v_mfma_f32_16x16x32_bf16 v[40:43], v[168:171], v[204:207], v[40:43]
	v_mfma_f32_16x16x32_bf16 v[32:35], v[176:179], v[204:207], v[32:35]
	v_mfma_f32_16x16x32_bf16 v[24:27], v[168:171], v[218:221], v[24:27]
	v_mfma_f32_16x16x32_bf16 v[16:19], v[176:179], v[218:221], v[16:19]
	v_mfma_f32_16x16x32_bf16 v[8:11], v[168:171], v[226:229], v[8:11]
	v_mfma_f32_16x16x32_bf16 v[0:3], v[176:179], v[226:229], v[0:3]
	v_mfma_f32_16x16x32_bf16 v[56:59], v[172:175], v[188:191], v[56:59]
	v_mfma_f32_16x16x32_bf16 v[48:51], v[180:183], v[188:191], v[48:51]
	v_mfma_f32_16x16x32_bf16 v[40:43], v[172:175], v[214:217], v[40:43]
	v_mfma_f32_16x16x32_bf16 v[32:35], v[180:183], v[214:217], v[32:35]
	v_mfma_f32_16x16x32_bf16 v[24:27], v[172:175], v[222:225], v[24:27]
	v_mfma_f32_16x16x32_bf16 v[16:19], v[180:183], v[222:225], v[16:19]
	v_mfma_f32_16x16x32_bf16 v[8:11], v[172:175], v[230:233], v[8:11]
	v_mfma_f32_16x16x32_bf16 v[0:3], v[180:183], v[230:233], v[0:3]
	s_barrier
	s_add_i32 s60, s60, 2
	s_add_u32 s46, s46, 0x100
	s_addc_u32 s47, s47, 0
	s_add_u32 s56, s56, 0x100
	s_addc_u32 s57, s57, 0
	s_cmp_gt_u32 s60, 13
	.p2align	6
